# first grid barrier: the 16 per-XCC census counters read with all loads in flight and one wait
# baseline (speedup 1.0000x reference)
.LBB0_101:
	v_readlane_b32 s7, v254, 55
	s_mov_b64 s[16:17], -1
	s_waitcnt lgkmcnt(0)
	v_readlane_b32 s12, v251, 16
	v_readlane_b32 s13, v251, 17
	s_nop 4
	global_load_dword v0, v64, s[12:13] sc1
	v_readlane_b32 s12, v251, 18
	v_readlane_b32 s13, v251, 19
	s_nop 4
	global_load_dword v1, v64, s[12:13] sc1
	v_readlane_b32 s12, v251, 20
	v_readlane_b32 s13, v251, 21
	s_nop 4
	global_load_dword v2, v64, s[12:13] sc1
	v_readlane_b32 s12, v251, 22
	v_readlane_b32 s13, v251, 23
	s_nop 4
	global_load_dword v3, v64, s[12:13] sc1
	v_readlane_b32 s12, v251, 24
	v_readlane_b32 s13, v251, 25
	s_nop 4
	global_load_dword v4, v64, s[12:13] sc1
	v_readlane_b32 s12, v251, 26
	v_readlane_b32 s13, v251, 27
	s_nop 4
	global_load_dword v5, v64, s[12:13] sc1
	v_readlane_b32 s12, v251, 28
	v_readlane_b32 s13, v251, 29
	s_nop 4
	global_load_dword v6, v64, s[12:13] sc1
	v_readlane_b32 s12, v251, 30
	v_readlane_b32 s13, v251, 31
	s_nop 4
	global_load_dword v7, v64, s[12:13] sc1
	v_readlane_b32 s12, v251, 32
	v_readlane_b32 s13, v251, 33
	s_nop 4
	global_load_dword v8, v64, s[12:13] sc1
	v_readlane_b32 s12, v251, 34
	v_readlane_b32 s13, v251, 35
	s_nop 4
	global_load_dword v9, v64, s[12:13] sc1
	v_readlane_b32 s12, v251, 36
	v_readlane_b32 s13, v251, 37
	s_nop 4
	global_load_dword v10, v64, s[12:13] sc1
	v_readlane_b32 s12, v251, 38
	v_readlane_b32 s13, v251, 39
	s_nop 4
	global_load_dword v11, v64, s[12:13] sc1
	v_readlane_b32 s12, v251, 40
	v_readlane_b32 s13, v251, 41
	s_nop 4
	global_load_dword v12, v64, s[12:13] sc1
	v_readlane_b32 s12, v251, 42
	v_readlane_b32 s13, v251, 43
	s_nop 4
	global_load_dword v13, v64, s[12:13] sc1
	v_readlane_b32 s12, v251, 44
	v_readlane_b32 s13, v251, 45
	s_nop 4
	global_load_dword v14, v64, s[12:13] sc1
	v_readlane_b32 s12, v251, 46
	v_readlane_b32 s13, v251, 47
	s_nop 4
	global_load_dword v15, v64, s[12:13] sc1
	s_mov_b64 s[12:13], -1
	s_waitcnt vmcnt(0)
	v_add_u32_e32 v16, v1, v0
	v_add_u32_e32 v16, v16, v2
	v_add_u32_e32 v16, v16, v3
	v_add_u32_e32 v16, v16, v4
	v_add_u32_e32 v16, v16, v5
	v_add_u32_e32 v16, v16, v6
	v_add_u32_e32 v16, v16, v7
	v_add_u32_e32 v16, v16, v8
	v_add_u32_e32 v16, v16, v9
	v_add_u32_e32 v16, v16, v10
	v_add_u32_e32 v16, v16, v11
	v_add_u32_e32 v16, v16, v12
	v_add_u32_e32 v16, v16, v13
	v_add_u32_e32 v16, v16, v14
	v_add_u32_e32 v16, v16, v15


	v_cmp_eq_u32_e32 vcc, s7, v16
	s_cbranch_vccnz .LBB0_100
	s_and_b32 s7, s6, 0xff
	s_cmp_eq_u32 s7, 0
	s_mov_b64 s[20:21], -1
	s_sleep 1
	s_cbranch_scc1 .LBB0_105
	s_and_b64 vcc, exec, s[20:21]
	s_cbranch_vccz .LBB0_100
